# grid barrier: XCD leader publishes the per-XCD release word before its own wait and cache invalidate (followers released earlier)
# speedup vs baseline: 1.0008x; 1.0008x over previous
.LBB0_672:
	s_or_b64 exec, exec, s[22:23]
	s_mov_b64 s[22:23], exec
	v_mbcnt_lo_u32_b32 v0, s22, 0
	v_mbcnt_hi_u32_b32 v0, s23, v0
	v_cmp_eq_u32_e32 vcc, 0, v0
	s_and_saveexec_b64 s[28:29], vcc
	s_cbranch_execz .Lxb_rel
	s_bcnt1_i32_b64 s2, s[22:23]
	v_readlane_b32 s4, v255, 9
	v_mov_b32_e32 v0, s2
	v_readlane_b32 s5, v255, 10
	s_nop 4
	global_atomic_add v185, v0, s[4:5]
.Lxb_rel:
	s_or_b64 exec, exec, s[28:29]
	s_waitcnt vmcnt(0)
	buffer_inv sc1
	s_branch .LBB0_21
